# out-projection epilogues of both layers: non-temporal hint on the residual-input loads
# baseline (speedup 1.0000x reference)
; #define LAS __attribute__((address_space(3)))
; DI int grow_of(int lrow, int seg) { return (lrow / SEG) * S + seg * SEG + (lrow % SEG); }
;     DI void fused(f32x4 (&acc)[2][2][4][2], const Unit& u, int wr, int wc, int fr, int fq, LAS unsigned char* lds, int wid, int lane) const {
;         LAS float* Pp = (LAS float*)lds;
;         LAS float* Sr = (LAS float*)(lds + 4096);
;         const int b = u.pm / TPB;
;         const int lrow0 = u.pm * BM + wr * 64 + fr;
;         const int col0 = u.pn * BM + wc * 32 + 8 * fq;
;         f32x4 gv[2][2];
; #pragma unroll
;         for (int bj = 0; bj < 2; ++bj)
; #pragma unroll
;             for (int n = 0; n < 2; ++n) gv[bj][n] = *(const f32x4*)(gate + b * 3072 + col0 + bj * HALF + 4 * n);
; #pragma unroll
;         for (int ai = 0; ai < 2; ++ai)
; #pragma unroll
;             for (int m = 0; m < 4; ++m) {
;                 const size_t off = (size_t)grow_of(lrow0 + ai * HALF + m * 16, seg) * D + col0;
;                 float sq = 0.f;
; #pragma unroll
;                 for (int bj = 0; bj < 2; ++bj)
; #pragma unroll
;                     for (int n = 0; n < 2; ++n) {
;                         const f32x4 xo = *(const f32x4*)(xin + off + bj * HALF + 4 * n);
;                         const f32x4 v = xo + gv[bj][n] * acc[ai][bj][m][n];
;                         acc[ai][bj][m][n] = v; sq += (v[0] * v[0] + v[1] * v[1]) + (v[2] * v[2] + v[3] * v[3]);
;                     }
;                 sq += __shfl_xor(sq, 16); sq += __shfl_xor(sq, 32);
;                 if (fq == 0) Pp[(ai * HALF + wr * 64 + m * 16 + fr) * 4 + wc] = sq;
;             }
.LBB0_822:
	s_lshl_b32 s46, s88, 8
	s_add_i32 s11, s46, s33
	v_and_b32_e32 v153, 64, v203
	v_or_b32_e32 v155, s11, v152
	v_xor_b32_e32 v152, 16, v203
	v_add_u32_e32 v153, 64, v153
	v_cmp_lt_i32_e32 vcc, v152, v153
	v_xor_b32_e32 v154, 32, v203
	s_ashr_i32 s6, s88, 31
	v_cndmask_b32_e32 v152, v203, v152, vcc
	v_cmp_lt_i32_e32 vcc, v154, v153
	s_lshr_b32 s6, s6, 28
	s_add_i32 s6, s88, s6
	v_cndmask_b32_e32 v153, v203, v154, vcc
	v_ashrrev_i32_e32 v154, 31, v155
	v_lshrrev_b32_e32 v154, 20, v154
	v_add_u32_e32 v156, v155, v154
	v_ashrrev_i32_e32 v156, 12, v156
	s_lshl_b32 s1, s39, 5
	s_lshr_b32 s6, s6, 4
	s_lshl_b32 s8, s0, 8
	v_lshlrev_b32_e32 v157, 13, v156
	v_mul_i32_i24_e32 v156, 0x1000, v156
	s_or_b32 s1, s8, s1
	s_mul_i32 s8, s6, 0xc00
	v_sub_u32_e32 v156, v155, v156
	v_lshrrev_b32_e32 v74, 1, v151
	s_ashr_i32 s9, s8, 31
	v_add3_u32 v156, v156, s84, v157
	v_and_or_b32 v148, v74, 24, s1
	s_lshl_b64 s[8:9], s[8:9], 2
	v_readlane_b32 s1, v251, 48
	v_ashrrev_i32_e32 v157, 31, v156
	s_add_u32 s8, s1, s8
	v_readlane_b32 s1, v251, 49
	v_ashrrev_i32_e32 v149, 31, v148
	v_lshlrev_b64 v[156:157], 12, v[156:157]
	s_addc_u32 s9, s1, s9
	v_lshlrev_b64 v[146:147], 2, v[148:149]
	v_lshl_add_u64 v[156:157], s[4:5], 0, v[156:157]
	v_lshl_add_u64 v[78:79], s[8:9], 0, v[146:147]
	v_lshl_add_u64 v[160:161], v[156:157], 0, v[146:147]
	s_waitcnt vmcnt(0)
	s_barrier
	global_load_dwordx4 v[90:93], v[78:79], off offset:16
	global_load_dwordx4 v[94:97], v[78:79], off
	global_load_dwordx4 v[74:77], v[78:79], off offset:528
	s_nop 0
	global_load_dwordx4 v[78:81], v[78:79], off offset:512
	s_nop 0
	global_load_dwordx4 v[156:159], v[160:161], off offset:16 nt
	global_load_dwordx4 v[172:175], v[160:161], off nt
	v_lshlrev_b32_e32 v152, 2, v152
	v_lshlrev_b32_e32 v153, 2, v153
	s_lshl_b32 s1, s39, 2
	v_and_b32_e32 v0, 63, v151
	s_add_i32 s8, s1, 0
	v_cmp_gt_u32_e32 vcc, 16, v0
	s_waitcnt vmcnt(0)
	v_pk_fma_f32 v[140:141], v[140:141], v[92:93], v[158:159]
	v_pk_fma_f32 v[144:145], v[144:145], v[96:97], v[174:175]
	v_pk_fma_f32 v[142:143], v[142:143], v[94:95], v[172:173]
	v_pk_fma_f32 v[138:139], v[138:139], v[90:91], v[156:157]
	v_mul_f32_e32 v163, v143, v143
	v_mul_f32_e32 v172, v145, v145
	v_mul_f32_e32 v156, v139, v139
	v_mul_f32_e32 v157, v141, v141
	v_fmac_f32_e32 v163, v142, v142
	v_fmac_f32_e32 v172, v144, v144
	v_fmac_f32_e32 v156, v138, v138
	v_fmac_f32_e32 v157, v140, v140
	v_add_f32_e32 v163, v163, v172
	v_add_f32_e32 v156, v156, v157
	v_add_f32_e32 v163, v163, v156
	global_load_dwordx4 v[156:159], v[160:161], off offset:528 nt
	global_load_dwordx4 v[172:175], v[160:161], off offset:512 nt
	s_waitcnt vmcnt(1)
	v_pk_fma_f32 v[132:133], v[132:133], v[76:77], v[158:159]
	s_waitcnt vmcnt(0)
	v_pk_fma_f32 v[136:137], v[136:137], v[80:81], v[174:175]
	v_pk_fma_f32 v[134:135], v[134:135], v[78:79], v[172:173]
	v_mul_f32_e32 v161, v137, v137
	v_mul_f32_e32 v160, v135, v135
	v_pk_fma_f32 v[130:131], v[130:131], v[74:75], v[156:157]
	v_fmac_f32_e32 v160, v134, v134
	v_fmac_f32_e32 v161, v136, v136
	v_mul_f32_e32 v156, v131, v131
	v_mul_f32_e32 v157, v133, v133
	v_add_f32_e32 v160, v160, v161
	v_fmac_f32_e32 v156, v130, v130
	v_fmac_f32_e32 v157, v132, v132
	v_add_f32_e32 v160, v163, v160
	v_add_f32_e32 v156, v156, v157
	v_add_f32_e32 v156, v160, v156
	ds_bpermute_b32 v157, v152, v156
	s_waitcnt lgkmcnt(0)
	v_add_f32_e32 v157, v156, v157
	ds_bpermute_b32 v158, v153, v157
	v_lshl_add_u32 v156, v150, 4, s8
	s_and_saveexec_b64 s[40:41], vcc
	s_cbranch_execz .LBB0_824
	s_waitcnt lgkmcnt(0)
	v_add_f32_e32 v157, v157, v158
	ds_write_b32 v156, v157
.LBB0_824:
	s_or_b64 exec, exec, s[40:41]
	v_or_b32_e32 v157, 16, v155
	s_waitcnt lgkmcnt(0)
	v_add_u32_e32 v158, v157, v154
	v_ashrrev_i32_e32 v158, 12, v158
	v_lshlrev_b32_e32 v159, 13, v158
	v_mul_i32_i24_e32 v158, 0x1000, v158
	v_sub_u32_e32 v157, v157, v158
	v_add3_u32 v158, v157, s84, v159
	v_ashrrev_i32_e32 v159, 31, v158
	v_lshlrev_b64 v[158:159], 12, v[158:159]
	v_lshl_add_u64 v[158:159], s[4:5], 0, v[158:159]
	v_lshl_add_u64 v[176:177], v[148:149], 2, v[158:159]
	global_load_dwordx4 v[158:161], v[176:177], off offset:16 nt
	global_load_dwordx4 v[172:175], v[176:177], off nt
	s_waitcnt vmcnt(1)
	v_pk_fma_f32 v[124:125], v[124:125], v[92:93], v[160:161]
	s_waitcnt vmcnt(0)
	v_pk_fma_f32 v[128:129], v[128:129], v[96:97], v[174:175]
	v_pk_fma_f32 v[126:127], v[126:127], v[94:95], v[172:173]
	v_pk_fma_f32 v[122:123], v[122:123], v[90:91], v[158:159]
	v_mul_f32_e32 v157, v127, v127
	v_mul_f32_e32 v163, v129, v129
	v_mul_f32_e32 v158, v123, v123
	v_mul_f32_e32 v159, v125, v125
	v_fmac_f32_e32 v157, v126, v126
	v_fmac_f32_e32 v163, v128, v128
	v_fmac_f32_e32 v158, v122, v122
	v_fmac_f32_e32 v159, v124, v124
	v_add_f32_e32 v157, v157, v163
	v_add_f32_e32 v158, v158, v159
	v_add_f32_e32 v157, v157, v158
	global_load_dwordx4 v[158:161], v[176:177], off offset:528 nt
	global_load_dwordx4 v[172:175], v[176:177], off offset:512 nt
	s_waitcnt vmcnt(1)
	v_pk_fma_f32 v[116:117], v[116:117], v[76:77], v[160:161]
	s_waitcnt vmcnt(0)
	v_pk_fma_f32 v[120:121], v[120:121], v[80:81], v[174:175]
	v_pk_fma_f32 v[118:119], v[118:119], v[78:79], v[172:173]
	v_mul_f32_e32 v172, v121, v121
	v_mul_f32_e32 v163, v119, v119
	v_pk_fma_f32 v[114:115], v[114:115], v[74:75], v[158:159]
	v_fmac_f32_e32 v163, v118, v118
	v_fmac_f32_e32 v172, v120, v120
	v_mul_f32_e32 v158, v115, v115
	v_mul_f32_e32 v159, v117, v117
	v_add_f32_e32 v163, v163, v172
	v_fmac_f32_e32 v158, v114, v114
	v_fmac_f32_e32 v159, v116, v116
	v_add_f32_e32 v157, v157, v163
	v_add_f32_e32 v158, v158, v159
	v_add_f32_e32 v157, v157, v158
	ds_bpermute_b32 v158, v152, v157
	s_waitcnt lgkmcnt(0)
	v_add_f32_e32 v157, v157, v158
	ds_bpermute_b32 v158, v153, v157
	s_and_saveexec_b64 s[40:41], vcc
	v_readlane_b32 s97, v250, 21
	v_readlane_b32 s33, v252, 10
	v_readlane_b32 s35, v250, 22
	v_readlane_b32 s78, v250, 23
	s_movk_i32 s79, 0x3ff
	s_movk_i32 s82, 0x90
	v_readlane_b32 s83, v250, 24
	s_movk_i32 s85, 0xdff
	s_movk_i32 s89, 0x2000
	s_mov_b32 s39, 0x3fb8aa3b
	s_mov_b32 s58, 0x42fc0000
	s_movk_i32 s59, 0x2400
	v_readlane_b32 s11, v250, 35
	v_readlane_b32 s6, v250, 59
	s_cbranch_execz .LBB0_826
	s_waitcnt lgkmcnt(0)
	v_add_f32_e32 v157, v157, v158
	ds_write_b32 v156, v157 offset:256
; DI int grow_of(int lrow, int seg) { return (lrow / SEG) * S + seg * SEG + (lrow % SEG); }
;     DI void fused(f32x4 (&acc)[2][2][4][2], const Unit& u, int wr, int wc, int fr, int fq, LAS unsigned char* lds, int wid, int lane) const {
;     ...
;         for (int ai = 0; ai < 2; ++ai)
; #pragma unroll
;             for (int m = 0; m < 4; ++m) {
;                 const size_t off = (size_t)grow_of(lrow0 + ai * HALF + m * 16, seg) * D + col0;
;                 float sq = 0.f;
; #pragma unroll
;                 for (int bj = 0; bj < 2; ++bj)
; #pragma unroll
;                     for (int n = 0; n < 2; ++n) {
;                         const f32x4 xo = *(const f32x4*)(xin + off + bj * HALF + 4 * n);
;                         const f32x4 v = xo + gv[bj][n] * acc[ai][bj][m][n];
;                         acc[ai][bj][m][n] = v; sq += (v[0] * v[0] + v[1] * v[1]) + (v[2] * v[2] + v[3] * v[3]);
;                     }
;                 sq += __shfl_xor(sq, 16); sq += __shfl_xor(sq, 32);
;                 if (fq == 0) Pp[(ai * HALF + wr * 64 + m * 16 + fr) * 4 + wc] = sq;
;             }
.LBB0_826:
	s_or_b64 exec, exec, s[40:41]
	v_or_b32_e32 v157, 32, v155
	s_waitcnt lgkmcnt(0)
	v_add_u32_e32 v158, v157, v154
	v_ashrrev_i32_e32 v158, 12, v158
	v_lshlrev_b32_e32 v159, 13, v158
	v_mul_i32_i24_e32 v158, 0x1000, v158
	v_sub_u32_e32 v157, v157, v158
	v_add3_u32 v158, v157, s84, v159
	v_ashrrev_i32_e32 v159, 31, v158
	v_lshlrev_b64 v[158:159], 12, v[158:159]
	v_lshl_add_u64 v[158:159], s[4:5], 0, v[158:159]
	v_lshl_add_u64 v[176:177], v[148:149], 2, v[158:159]
	global_load_dwordx4 v[158:161], v[176:177], off offset:16 nt
	global_load_dwordx4 v[172:175], v[176:177], off nt
	s_waitcnt vmcnt(1)
	v_pk_fma_f32 v[108:109], v[108:109], v[92:93], v[160:161]
	s_waitcnt vmcnt(0)
	v_pk_fma_f32 v[112:113], v[112:113], v[96:97], v[174:175]
	v_pk_fma_f32 v[110:111], v[110:111], v[94:95], v[172:173]
	v_pk_fma_f32 v[106:107], v[106:107], v[90:91], v[158:159]
	v_mul_f32_e32 v157, v111, v111
	v_mul_f32_e32 v163, v113, v113
	v_mul_f32_e32 v158, v107, v107
	v_mul_f32_e32 v159, v109, v109
	v_fmac_f32_e32 v157, v110, v110
	v_fmac_f32_e32 v163, v112, v112
	v_fmac_f32_e32 v158, v106, v106
	v_fmac_f32_e32 v159, v108, v108
	v_add_f32_e32 v157, v157, v163
	v_add_f32_e32 v158, v158, v159
	v_add_f32_e32 v157, v157, v158
	global_load_dwordx4 v[158:161], v[176:177], off offset:528 nt
	global_load_dwordx4 v[172:175], v[176:177], off offset:512 nt
	s_waitcnt vmcnt(1)
	v_pk_fma_f32 v[100:101], v[100:101], v[76:77], v[160:161]
	s_waitcnt vmcnt(0)
	v_pk_fma_f32 v[104:105], v[104:105], v[80:81], v[174:175]
	v_pk_fma_f32 v[102:103], v[102:103], v[78:79], v[172:173]
	v_mul_f32_e32 v172, v105, v105
	v_mul_f32_e32 v163, v103, v103
	v_pk_fma_f32 v[98:99], v[98:99], v[74:75], v[158:159]
	v_fmac_f32_e32 v163, v102, v102
	v_fmac_f32_e32 v172, v104, v104
	v_mul_f32_e32 v158, v99, v99
	v_mul_f32_e32 v159, v101, v101
	v_add_f32_e32 v163, v163, v172
	v_fmac_f32_e32 v158, v98, v98
	v_fmac_f32_e32 v159, v100, v100
	v_add_f32_e32 v157, v157, v163
	v_add_f32_e32 v158, v158, v159
	v_add_f32_e32 v157, v157, v158
	ds_bpermute_b32 v158, v152, v157
	s_waitcnt lgkmcnt(0)
	v_add_f32_e32 v157, v157, v158
	ds_bpermute_b32 v158, v153, v157
	s_and_saveexec_b64 s[40:41], vcc
	s_cbranch_execz .LBB0_828
	s_waitcnt lgkmcnt(0)
	v_add_f32_e32 v157, v157, v158
	ds_write_b32 v156, v157 offset:512
.LBB0_828:
	s_or_b64 exec, exec, s[40:41]
	v_or_b32_e32 v157, 48, v155
	v_add_u32_e32 v154, v157, v154
	v_ashrrev_i32_e32 v154, 12, v154
	s_waitcnt lgkmcnt(0)
	v_lshlrev_b32_e32 v158, 13, v154
	v_mul_i32_i24_e32 v154, 0x1000, v154
	v_sub_u32_e32 v154, v157, v154
	v_add3_u32 v158, v154, s84, v158
	v_ashrrev_i32_e32 v159, 31, v158
	v_lshlrev_b64 v[158:159], 12, v[158:159]
	v_lshl_add_u64 v[158:159], s[4:5], 0, v[158:159]
	v_lshl_add_u64 v[176:177], v[148:149], 2, v[158:159]
	global_load_dwordx4 v[158:161], v[176:177], off offset:16 nt
	global_load_dwordx4 v[172:175], v[176:177], off nt
	s_waitcnt vmcnt(1)
	v_pk_fma_f32 v[84:85], v[84:85], v[92:93], v[160:161]
	s_waitcnt vmcnt(0)
	v_pk_fma_f32 v[88:89], v[88:89], v[96:97], v[174:175]
	v_pk_fma_f32 v[86:87], v[86:87], v[94:95], v[172:173]
	v_mul_f32_e32 v157, v89, v89
	v_mul_f32_e32 v154, v87, v87
	v_fmac_f32_e32 v154, v86, v86
	v_fmac_f32_e32 v157, v88, v88
	v_pk_fma_f32 v[82:83], v[82:83], v[90:91], v[158:159]
	v_add_f32_e32 v154, v154, v157
	v_mul_f32_e32 v157, v83, v83
	v_mul_f32_e32 v158, v85, v85
	v_fmac_f32_e32 v157, v82, v82
	v_fmac_f32_e32 v158, v84, v84
	v_add_f32_e32 v157, v157, v158
	global_load_dwordx4 v[158:161], v[176:177], off offset:528 nt
	global_load_dwordx4 v[172:175], v[176:177], off offset:512 nt
	v_add_f32_e32 v154, v154, v157
	s_waitcnt vmcnt(1)
	v_pk_fma_f32 v[68:69], v[68:69], v[76:77], v[160:161]
	s_waitcnt vmcnt(0)
	v_pk_fma_f32 v[72:73], v[72:73], v[80:81], v[174:175]
	v_pk_fma_f32 v[70:71], v[70:71], v[78:79], v[172:173]
	v_mul_f32_e32 v163, v73, v73
	v_mul_f32_e32 v157, v71, v71
	v_fmac_f32_e32 v157, v70, v70
	v_fmac_f32_e32 v163, v72, v72
	v_add_f32_e32 v157, v157, v163
	v_pk_fma_f32 v[66:67], v[66:67], v[74:75], v[158:159]
	v_add_f32_e32 v154, v154, v157
	v_mul_f32_e32 v157, v67, v67
	v_mul_f32_e32 v158, v69, v69
	v_fmac_f32_e32 v157, v66, v66
	v_fmac_f32_e32 v158, v68, v68
	v_add_f32_e32 v157, v157, v158
	v_add_f32_e32 v154, v154, v157
	ds_bpermute_b32 v157, v152, v154
	s_waitcnt lgkmcnt(0)
	v_add_f32_e32 v154, v154, v157
	ds_bpermute_b32 v157, v153, v154
	s_and_saveexec_b64 s[40:41], vcc
	s_cbranch_execz .LBB0_830
	s_waitcnt lgkmcnt(0)
	v_add_f32_e32 v154, v154, v157
	ds_write_b32 v156, v154 offset:768
; DI int grow_of(int lrow, int seg) { return (lrow / SEG) * S + seg * SEG + (lrow % SEG); }
;     DI void fused(f32x4 (&acc)[2][2][4][2], const Unit& u, int wr, int wc, int fr, int fq, LAS unsigned char* lds, int wid, int lane) const {
;     ...
;         for (int ai = 0; ai < 2; ++ai)
; #pragma unroll
;             for (int m = 0; m < 4; ++m) {
;                 const size_t off = (size_t)grow_of(lrow0 + ai * HALF + m * 16, seg) * D + col0;
;                 float sq = 0.f;
; #pragma unroll
;                 for (int bj = 0; bj < 2; ++bj)
; #pragma unroll
;                     for (int n = 0; n < 2; ++n) {
;                         const f32x4 xo = *(const f32x4*)(xin + off + bj * HALF + 4 * n);
;                         const f32x4 v = xo + gv[bj][n] * acc[ai][bj][m][n];
;                         acc[ai][bj][m][n] = v; sq += (v[0] * v[0] + v[1] * v[1]) + (v[2] * v[2] + v[3] * v[3]);
;                     }
;                 sq += __shfl_xor(sq, 16); sq += __shfl_xor(sq, 32);
;                 if (fq == 0) Pp[(ai * HALF + wr * 64 + m * 16 + fr) * 4 + wc] = sq;
;             }
.LBB0_830:
	s_or_b64 exec, exec, s[40:41]
	s_waitcnt lgkmcnt(0)
	v_add_u32_e32 v157, 0x80, v155
	v_ashrrev_i32_e32 v158, 31, v157
	v_lshrrev_b32_e32 v158, 20, v158
	v_add_u32_e32 v158, v157, v158
	v_ashrrev_i32_e32 v158, 12, v158
	v_lshlrev_b32_e32 v159, 13, v158
	v_mul_i32_i24_e32 v158, 0x1000, v158
	v_sub_u32_e32 v157, v157, v158
	v_add3_u32 v158, v157, s84, v159
	v_ashrrev_i32_e32 v159, 31, v158
	v_lshlrev_b64 v[158:159], 12, v[158:159]
	v_lshl_add_u64 v[158:159], s[4:5], 0, v[158:159]
	v_lshl_add_u64 v[176:177], v[148:149], 2, v[158:159]
	global_load_dwordx4 v[158:161], v[176:177], off offset:16 nt
	global_load_dwordx4 v[172:175], v[176:177], off nt
	v_add_u32_e32 v154, 0x80, v150
	s_waitcnt vmcnt(1)
	v_pk_fma_f32 v[60:61], v[60:61], v[92:93], v[160:161]
	s_waitcnt vmcnt(0)
	v_pk_fma_f32 v[64:65], v[64:65], v[96:97], v[174:175]
	v_pk_fma_f32 v[62:63], v[62:63], v[94:95], v[172:173]
	v_pk_fma_f32 v[58:59], v[58:59], v[90:91], v[158:159]
	v_mul_f32_e32 v157, v63, v63
	v_mul_f32_e32 v163, v65, v65
	v_mul_f32_e32 v158, v59, v59
	v_mul_f32_e32 v159, v61, v61
	v_fmac_f32_e32 v157, v62, v62
	v_fmac_f32_e32 v163, v64, v64
	v_fmac_f32_e32 v158, v58, v58
	v_fmac_f32_e32 v159, v60, v60
	v_add_f32_e32 v157, v157, v163
	v_add_f32_e32 v158, v158, v159
	v_add_f32_e32 v157, v157, v158
	global_load_dwordx4 v[158:161], v[176:177], off offset:528 nt
	global_load_dwordx4 v[172:175], v[176:177], off offset:512 nt
	s_waitcnt vmcnt(1)
	v_pk_fma_f32 v[52:53], v[52:53], v[76:77], v[160:161]
	s_waitcnt vmcnt(0)
	v_pk_fma_f32 v[56:57], v[56:57], v[80:81], v[174:175]
	v_pk_fma_f32 v[54:55], v[54:55], v[78:79], v[172:173]
	v_mul_f32_e32 v172, v57, v57
	v_mul_f32_e32 v163, v55, v55
	v_pk_fma_f32 v[50:51], v[50:51], v[74:75], v[158:159]
	v_fmac_f32_e32 v163, v54, v54
	v_fmac_f32_e32 v172, v56, v56
	v_mul_f32_e32 v158, v51, v51
	v_mul_f32_e32 v159, v53, v53
	v_add_f32_e32 v163, v163, v172
	v_fmac_f32_e32 v158, v50, v50
	v_fmac_f32_e32 v159, v52, v52
	v_add_f32_e32 v157, v157, v163
	v_add_f32_e32 v158, v158, v159
	v_add_f32_e32 v157, v157, v158
	ds_bpermute_b32 v158, v152, v157
	s_waitcnt lgkmcnt(0)
	v_add_f32_e32 v157, v157, v158
	ds_bpermute_b32 v158, v153, v157
	s_and_saveexec_b64 s[40:41], vcc
	s_cbranch_execz .LBB0_832
	v_lshl_add_u32 v159, v154, 4, s8
	s_waitcnt lgkmcnt(0)
	v_add_f32_e32 v157, v157, v158
	ds_write_b32 v159, v157
.LBB0_832:
	s_or_b64 exec, exec, s[40:41]
	v_add_u32_e32 v157, 0x90, v155
	s_waitcnt lgkmcnt(0)
	v_ashrrev_i32_e32 v158, 31, v157
	v_lshrrev_b32_e32 v158, 20, v158
	v_add_u32_e32 v158, v157, v158
	v_ashrrev_i32_e32 v158, 12, v158
	v_lshlrev_b32_e32 v159, 13, v158
	v_mul_i32_i24_e32 v158, 0x1000, v158
	v_sub_u32_e32 v157, v157, v158
	v_add3_u32 v158, v157, s84, v159
	v_ashrrev_i32_e32 v159, 31, v158
	v_lshlrev_b64 v[158:159], 12, v[158:159]
	v_lshl_add_u64 v[158:159], s[4:5], 0, v[158:159]
	v_lshl_add_u64 v[176:177], v[148:149], 2, v[158:159]
	global_load_dwordx4 v[158:161], v[176:177], off offset:16 nt
	global_load_dwordx4 v[172:175], v[176:177], off nt
	s_waitcnt vmcnt(1)
	v_pk_fma_f32 v[44:45], v[44:45], v[92:93], v[160:161]
	s_waitcnt vmcnt(0)
	v_pk_fma_f32 v[48:49], v[48:49], v[96:97], v[174:175]
	v_pk_fma_f32 v[46:47], v[46:47], v[94:95], v[172:173]
	v_pk_fma_f32 v[42:43], v[42:43], v[90:91], v[158:159]
	v_mul_f32_e32 v157, v47, v47
	v_mul_f32_e32 v163, v49, v49
	v_mul_f32_e32 v158, v43, v43
	v_mul_f32_e32 v159, v45, v45
	v_fmac_f32_e32 v157, v46, v46
	v_fmac_f32_e32 v163, v48, v48
	v_fmac_f32_e32 v158, v42, v42
	v_fmac_f32_e32 v159, v44, v44
	v_add_f32_e32 v157, v157, v163
	v_add_f32_e32 v158, v158, v159
	v_add_f32_e32 v157, v157, v158
	global_load_dwordx4 v[158:161], v[176:177], off offset:528 nt
	global_load_dwordx4 v[172:175], v[176:177], off offset:512 nt
	s_waitcnt vmcnt(1)
	v_pk_fma_f32 v[36:37], v[36:37], v[76:77], v[160:161]
	s_waitcnt vmcnt(0)
	v_pk_fma_f32 v[40:41], v[40:41], v[80:81], v[174:175]
	v_pk_fma_f32 v[38:39], v[38:39], v[78:79], v[172:173]
	v_mul_f32_e32 v172, v41, v41
	v_mul_f32_e32 v163, v39, v39
	v_pk_fma_f32 v[34:35], v[34:35], v[74:75], v[158:159]
	v_fmac_f32_e32 v163, v38, v38
	v_fmac_f32_e32 v172, v40, v40
	v_mul_f32_e32 v158, v35, v35
	v_mul_f32_e32 v159, v37, v37
	v_add_f32_e32 v163, v163, v172
	v_fmac_f32_e32 v158, v34, v34
	v_fmac_f32_e32 v159, v36, v36
	v_add_f32_e32 v157, v157, v163
	v_add_f32_e32 v158, v158, v159
	v_add_f32_e32 v157, v157, v158
	ds_bpermute_b32 v158, v152, v157
	s_waitcnt lgkmcnt(0)
	v_add_f32_e32 v157, v157, v158
	ds_bpermute_b32 v158, v153, v157
	s_and_saveexec_b64 s[40:41], vcc
	s_cbranch_execz .LBB0_834
	s_waitcnt lgkmcnt(0)
	v_add_f32_e32 v157, v157, v158
	ds_write_b32 v156, v157 offset:2304
; DI int grow_of(int lrow, int seg) { return (lrow / SEG) * S + seg * SEG + (lrow % SEG); }
;     DI void fused(f32x4 (&acc)[2][2][4][2], const Unit& u, int wr, int wc, int fr, int fq, LAS unsigned char* lds, int wid, int lane) const {
;     ...
;         for (int ai = 0; ai < 2; ++ai)
; #pragma unroll
;             for (int m = 0; m < 4; ++m) {
;                 const size_t off = (size_t)grow_of(lrow0 + ai * HALF + m * 16, seg) * D + col0;
;                 float sq = 0.f;
; #pragma unroll
;                 for (int bj = 0; bj < 2; ++bj)
; #pragma unroll
;                     for (int n = 0; n < 2; ++n) {
;                         const f32x4 xo = *(const f32x4*)(xin + off + bj * HALF + 4 * n);
;                         const f32x4 v = xo + gv[bj][n] * acc[ai][bj][m][n];
;                         acc[ai][bj][m][n] = v; sq += (v[0] * v[0] + v[1] * v[1]) + (v[2] * v[2] + v[3] * v[3]);
;                     }
;                 sq += __shfl_xor(sq, 16); sq += __shfl_xor(sq, 32);
;                 if (fq == 0) Pp[(ai * HALF + wr * 64 + m * 16 + fr) * 4 + wc] = sq;
;             }
.LBB0_834:
	s_or_b64 exec, exec, s[40:41]
	v_add_u32_e32 v157, 0xa0, v155
	s_waitcnt lgkmcnt(0)
	v_ashrrev_i32_e32 v158, 31, v157
	v_lshrrev_b32_e32 v158, 20, v158
	v_add_u32_e32 v158, v157, v158
	v_ashrrev_i32_e32 v158, 12, v158
	v_lshlrev_b32_e32 v159, 13, v158
	v_mul_i32_i24_e32 v158, 0x1000, v158
	v_sub_u32_e32 v157, v157, v158
	v_add3_u32 v158, v157, s84, v159
	v_ashrrev_i32_e32 v159, 31, v158
	v_lshlrev_b64 v[158:159], 12, v[158:159]
	v_lshl_add_u64 v[158:159], s[4:5], 0, v[158:159]
	v_lshl_add_u64 v[176:177], v[148:149], 2, v[158:159]
	global_load_dwordx4 v[158:161], v[176:177], off offset:16 nt
	global_load_dwordx4 v[172:175], v[176:177], off nt
	s_waitcnt vmcnt(1)
	v_pk_fma_f32 v[28:29], v[28:29], v[92:93], v[160:161]
	s_waitcnt vmcnt(0)
	v_pk_fma_f32 v[32:33], v[32:33], v[96:97], v[174:175]
	v_pk_fma_f32 v[30:31], v[30:31], v[94:95], v[172:173]
	v_pk_fma_f32 v[26:27], v[26:27], v[90:91], v[158:159]
	v_mul_f32_e32 v157, v31, v31
	v_mul_f32_e32 v163, v33, v33
	v_mul_f32_e32 v158, v27, v27
	v_mul_f32_e32 v159, v29, v29
	v_fmac_f32_e32 v157, v30, v30
	v_fmac_f32_e32 v163, v32, v32
	v_fmac_f32_e32 v158, v26, v26
	v_fmac_f32_e32 v159, v28, v28
	v_add_f32_e32 v157, v157, v163
	v_add_f32_e32 v158, v158, v159
	v_add_f32_e32 v157, v157, v158
	global_load_dwordx4 v[158:161], v[176:177], off offset:528 nt
	global_load_dwordx4 v[172:175], v[176:177], off offset:512 nt
	s_waitcnt vmcnt(1)
	v_pk_fma_f32 v[20:21], v[20:21], v[76:77], v[160:161]
	s_waitcnt vmcnt(0)
	v_pk_fma_f32 v[24:25], v[24:25], v[80:81], v[174:175]
	v_pk_fma_f32 v[22:23], v[22:23], v[78:79], v[172:173]
	v_mul_f32_e32 v172, v25, v25
	v_mul_f32_e32 v163, v23, v23
	v_pk_fma_f32 v[18:19], v[18:19], v[74:75], v[158:159]
	v_fmac_f32_e32 v163, v22, v22
	v_fmac_f32_e32 v172, v24, v24
	v_mul_f32_e32 v158, v19, v19
	v_mul_f32_e32 v159, v21, v21
	v_add_f32_e32 v163, v163, v172
	v_fmac_f32_e32 v158, v18, v18
	v_fmac_f32_e32 v159, v20, v20
	v_add_f32_e32 v157, v157, v163
	v_add_f32_e32 v158, v158, v159
	v_add_f32_e32 v157, v157, v158
	ds_bpermute_b32 v158, v152, v157
	s_waitcnt lgkmcnt(0)
	v_add_f32_e32 v157, v157, v158
	ds_bpermute_b32 v158, v153, v157
	s_and_saveexec_b64 s[40:41], vcc
	s_cbranch_execz .LBB0_836
	s_waitcnt lgkmcnt(0)
	v_add_f32_e32 v157, v157, v158
	ds_write_b32 v156, v157 offset:2560
.LBB0_836:
	s_or_b64 exec, exec, s[40:41]
	v_add_u32_e32 v155, 0xb0, v155
	v_ashrrev_i32_e32 v157, 31, v155
	v_lshrrev_b32_e32 v157, 20, v157
	v_add_u32_e32 v157, v155, v157
	v_ashrrev_i32_e32 v157, 12, v157
	s_waitcnt lgkmcnt(0)
	v_lshlrev_b32_e32 v158, 13, v157
	v_mul_i32_i24_e32 v157, 0x1000, v157
	v_sub_u32_e32 v155, v155, v157
	v_add3_u32 v158, v155, s84, v158
	v_ashrrev_i32_e32 v159, 31, v158
	v_lshlrev_b64 v[158:159], 12, v[158:159]
	v_lshl_add_u64 v[158:159], s[4:5], 0, v[158:159]
	v_lshl_add_u64 v[148:149], v[148:149], 2, v[158:159]
	global_load_dwordx4 v[158:161], v[148:149], off offset:16 nt
	global_load_dwordx4 v[172:175], v[148:149], off nt
	s_waitcnt vmcnt(1)
	v_pk_fma_f32 v[92:93], v[12:13], v[92:93], v[160:161]
	s_waitcnt vmcnt(0)
	v_pk_fma_f32 v[96:97], v[16:17], v[96:97], v[174:175]
	v_pk_fma_f32 v[94:95], v[14:15], v[94:95], v[172:173]
	v_pk_fma_f32 v[90:91], v[10:11], v[90:91], v[158:159]
	v_mul_f32_e32 v14, v95, v95
	v_mul_f32_e32 v15, v97, v97
	v_mul_f32_e32 v10, v91, v91
	v_mul_f32_e32 v11, v93, v93
	v_fmac_f32_e32 v14, v94, v94
	v_fmac_f32_e32 v15, v96, v96
	v_fmac_f32_e32 v10, v90, v90
	v_fmac_f32_e32 v11, v92, v92
	v_add_f32_e32 v14, v14, v15
	v_add_f32_e32 v10, v10, v11
	v_add_f32_e32 v155, v14, v10
	global_load_dwordx4 v[10:13], v[148:149], off offset:528 nt
	global_load_dwordx4 v[14:17], v[148:149], off offset:512 nt
	s_waitcnt vmcnt(1)
	v_pk_fma_f32 v[76:77], v[4:5], v[76:77], v[12:13]
	s_waitcnt vmcnt(0)
	v_pk_fma_f32 v[80:81], v[8:9], v[80:81], v[16:17]
	v_pk_fma_f32 v[78:79], v[6:7], v[78:79], v[14:15]
	v_mul_f32_e32 v7, v81, v81
	v_mul_f32_e32 v6, v79, v79
	v_pk_fma_f32 v[74:75], v[2:3], v[74:75], v[10:11]
	v_fmac_f32_e32 v6, v78, v78
	v_fmac_f32_e32 v7, v80, v80
	v_mul_f32_e32 v2, v75, v75
	v_mul_f32_e32 v3, v77, v77
	v_add_f32_e32 v6, v6, v7
	v_fmac_f32_e32 v2, v74, v74
	v_fmac_f32_e32 v3, v76, v76
	v_add_f32_e32 v6, v155, v6
	v_add_f32_e32 v2, v2, v3
	v_add_f32_e32 v2, v6, v2
	ds_bpermute_b32 v3, v152, v2
	s_waitcnt lgkmcnt(0)
	v_add_f32_e32 v2, v2, v3
	ds_bpermute_b32 v3, v153, v2
	s_and_saveexec_b64 s[40:41], vcc
	s_cbranch_execz .LBB0_838
	s_waitcnt lgkmcnt(0)
	v_add_f32_e32 v2, v2, v3
	ds_write_b32 v156, v2 offset:2816
